# SwiGLU/ProjGate: first K-iteration of every non-first unit runs from a peeled copy (first MFMA per accumulator takes C=0, no zero-init; its two LDS-DMA waits leave the previous epilogue's 8 stores in
# speedup vs baseline: 1.0081x; 1.0015x over previous
; template <class Epi, class Sched, bool ALIGN_EPI = false, bool SP2 = false>
; __device__ __forceinline__ void gemm_phase(PG8_LAS unsigned char* lds, const Gemm g, const Sched& S, const Epi& E) {
;     ...
;         const bool has_next = S.next(ui + 1, nxt);
;         const char* nA = has_next ? (const char*)g.A + (size_t)nxt.pm * tstep : cA; const char* nB = has_next ? (const char*)g.Bt + (size_t)nxt.pn * tstep : cB;
;         for (int t = 0; t < nt; t += 2) {
;             const bool last = (t == nt - 2);
;             const char* a1 = cA + (size_t)(t + 1) * kstep;
;             const char* a2 = last ? nA : cA + (size_t)(t + 2) * kstep; const char* b2 = last ? nB : cB + (size_t)(t + 2) * kstep;
;             const char* a3 = a2 + kstep; const char* b3 = b2 + kstep;
;     ...
; #pragma unroll
;         for (int a = 0; a < 2; ++a)
; #pragma unroll
;             for (int b = 0; b < 2; ++b)
; #pragma unroll
;                 for (int m = 0; m < 4; ++m)
; #pragma unroll
;                     for (int n = 0; n < 2; ++n) acc[a][b][m][n] = (f32x4){0.f, 0.f, 0.f, 0.f};
.LBB0_341:
	s_ashr_i32 s21, s20, 31
	s_lshl_b64 s[22:23], s[20:21], 19
	s_add_u32 s22, s2, s22
	s_addc_u32 s23, s3, s23
	s_and_b64 s[40:41], s[38:39], exec
	s_cselect_b32 s21, s23, s1
	s_cselect_b32 s45, s22, s0
	s_ashr_i32 s19, s18, 31
	s_lshl_b64 s[40:41], s[18:19], 19
	s_add_u32 s40, s8, s40
	s_addc_u32 s41, s48, s41
	s_and_b64 s[42:43], s[38:39], exec
	s_cselect_b32 s19, s41, s5
	s_cselect_b32 s46, s40, s4
	s_add_u32 s0, s0, 0x40080
	s_addc_u32 s1, s1, 0
	s_add_u32 s47, s4, 0x100
	s_addc_u32 s58, s5, 0
	s_mov_b32 s59, -2
	s_cmp_lg_u32 s56, 1
	s_cbranch_scc1 .Lpeel_pg
	s_waitcnt vmcnt(0)
	v_mov_b32_e32 v0, 0
	v_mov_b32_e32 v1, v0
	v_mov_b32_e32 v2, v0
	v_mov_b32_e32 v3, v0
	v_mov_b32_e32 v4, v0
	v_mov_b32_e32 v5, v0
	v_mov_b32_e32 v6, v0
	v_mov_b32_e32 v7, v0
	v_mov_b32_e32 v16, v0
	v_mov_b32_e32 v17, v0
	v_mov_b32_e32 v18, v0
	v_mov_b32_e32 v19, v0
	v_mov_b32_e32 v20, v0
	v_mov_b32_e32 v21, v0
	v_mov_b32_e32 v22, v0
	v_mov_b32_e32 v23, v0
	v_mov_b32_e32 v36, v0
	v_mov_b32_e32 v37, v0
	v_mov_b32_e32 v38, v0
	v_mov_b32_e32 v39, v0
	v_mov_b32_e32 v40, v0
	v_mov_b32_e32 v41, v0
	v_mov_b32_e32 v42, v0
	v_mov_b32_e32 v43, v0
	v_mov_b32_e32 v52, v0
	v_mov_b32_e32 v53, v0
	v_mov_b32_e32 v54, v0
	v_mov_b32_e32 v55, v0
	v_mov_b32_e32 v56, v0
	v_mov_b32_e32 v57, v0
	v_mov_b32_e32 v58, v0
	v_mov_b32_e32 v59, v0
	v_mov_b32_e32 v8, v0
	v_mov_b32_e32 v9, v0
	v_mov_b32_e32 v10, v0
	v_mov_b32_e32 v11, v0
	v_mov_b32_e32 v12, v0
	v_mov_b32_e32 v13, v0
	v_mov_b32_e32 v14, v0
	v_mov_b32_e32 v15, v0
	v_mov_b32_e32 v24, v0
	v_mov_b32_e32 v25, v0
	v_mov_b32_e32 v26, v0
	v_mov_b32_e32 v27, v0
	v_mov_b32_e32 v28, v0
	v_mov_b32_e32 v29, v0
	v_mov_b32_e32 v30, v0
	v_mov_b32_e32 v31, v0
	v_mov_b32_e32 v44, v0
	v_mov_b32_e32 v45, v0
	v_mov_b32_e32 v46, v0
	v_mov_b32_e32 v47, v0
	v_mov_b32_e32 v48, v0
	v_mov_b32_e32 v49, v0
	v_mov_b32_e32 v50, v0
	v_mov_b32_e32 v51, v0
	v_mov_b32_e32 v60, v0
	v_mov_b32_e32 v61, v0
	v_mov_b32_e32 v62, v0
	v_mov_b32_e32 v63, v0
	v_mov_b32_e32 v64, v0
	v_mov_b32_e32 v65, v0
	v_mov_b32_e32 v66, v0
	v_mov_b32_e32 v67, v0
	v_mov_b32_e32 v68, v0
	v_mov_b32_e32 v69, v0
	v_mov_b32_e32 v70, v0
	v_mov_b32_e32 v71, v0
	v_mov_b32_e32 v72, v0
	v_mov_b32_e32 v73, v0
	v_mov_b32_e32 v74, v0
	v_mov_b32_e32 v75, v0
	v_mov_b32_e32 v84, v0
	v_mov_b32_e32 v85, v0
	v_mov_b32_e32 v86, v0
	v_mov_b32_e32 v87, v0
	v_mov_b32_e32 v88, v0
	v_mov_b32_e32 v89, v0
	v_mov_b32_e32 v90, v0
	v_mov_b32_e32 v91, v0
	v_mov_b32_e32 v100, v0
	v_mov_b32_e32 v101, v0
	v_mov_b32_e32 v102, v0
	v_mov_b32_e32 v103, v0
	v_mov_b32_e32 v104, v0
	v_mov_b32_e32 v105, v0
	v_mov_b32_e32 v106, v0
	v_mov_b32_e32 v107, v0
	v_mov_b32_e32 v116, v0
	v_mov_b32_e32 v117, v0
	v_mov_b32_e32 v118, v0
	v_mov_b32_e32 v119, v0
	v_mov_b32_e32 v120, v0
	v_mov_b32_e32 v121, v0
	v_mov_b32_e32 v122, v0
	v_mov_b32_e32 v123, v0
	v_mov_b32_e32 v76, v0
	v_mov_b32_e32 v77, v0
	v_mov_b32_e32 v78, v0
	v_mov_b32_e32 v79, v0
	v_mov_b32_e32 v80, v0
	v_mov_b32_e32 v81, v0
	v_mov_b32_e32 v82, v0
	v_mov_b32_e32 v83, v0
	v_mov_b32_e32 v92, v0
	v_mov_b32_e32 v93, v0
	v_mov_b32_e32 v94, v0
	v_mov_b32_e32 v95, v0
	v_mov_b32_e32 v96, v0
	v_mov_b32_e32 v97, v0
	v_mov_b32_e32 v98, v0
	v_mov_b32_e32 v99, v0
	v_mov_b32_e32 v108, v0
	v_mov_b32_e32 v109, v0
	v_mov_b32_e32 v110, v0
	v_mov_b32_e32 v111, v0
	v_mov_b32_e32 v112, v0
	v_mov_b32_e32 v113, v0
	v_mov_b32_e32 v114, v0
	v_mov_b32_e32 v115, v0
	v_mov_b32_e32 v124, v0
	v_mov_b32_e32 v125, v0
	v_mov_b32_e32 v126, v0
	v_mov_b32_e32 v127, v0
	v_mov_b32_e32 v128, v0
	v_mov_b32_e32 v129, v0
	v_mov_b32_e32 v130, v0
	v_mov_b32_e32 v131, v0

; template <class Epi, class Sched, bool ALIGN_EPI = false, bool SP2 = false>
; __device__ __forceinline__ void gemm_phase(PG8_LAS unsigned char* lds, const Gemm g, const Sched& S, const Epi& E) {
;     ...
;         const bool has_next = S.next(ui + 1, nxt);
;         const char* nA = has_next ? (const char*)g.A + (size_t)nxt.pm * tstep : cA; const char* nB = has_next ? (const char*)g.Bt + (size_t)nxt.pn * tstep : cB;
;         for (int t = 0; t < nt; t += 2) {
;             const bool last = (t == nt - 2);
;             const char* a1 = cA + (size_t)(t + 1) * kstep;
;             const char* a2 = last ? nA : cA + (size_t)(t + 2) * kstep; const char* b2 = last ? nB : cB + (size_t)(t + 2) * kstep;
;             const char* a3 = a2 + kstep; const char* b3 = b2 + kstep;
;     ...
; #pragma unroll
;         for (int a = 0; a < 2; ++a)
; #pragma unroll
;             for (int b = 0; b < 2; ++b)
; #pragma unroll
;                 for (int m = 0; m < 4; ++m)
; #pragma unroll
;                     for (int n = 0; n < 2; ++n) acc[a][b][m][n] = (f32x4){0.f, 0.f, 0.f, 0.f};
.LBB0_622:
	s_ashr_i32 s17, s16, 31
	s_lshl_b64 s[18:19], s[16:17], 19
	s_add_u32 s18, s2, s18
	s_addc_u32 s19, s3, s19
	s_and_b64 s[20:21], s[38:39], exec
	s_cselect_b32 s17, s19, s1
	s_cselect_b32 s53, s18, s0
	s_ashr_i32 s15, s14, 31
	s_lshl_b64 s[20:21], s[14:15], 19
	s_add_u32 s20, s8, s20
	s_addc_u32 s21, s42, s21
	s_and_b64 s[40:41], s[38:39], exec
	s_cselect_b32 s15, s21, s23
	s_cselect_b32 s54, s20, s22
	s_add_u32 s0, s0, 0x40080
	s_addc_u32 s1, s1, 0
	s_add_u32 s55, s22, 0x100
	s_addc_u32 s56, s23, 0
	s_mov_b32 s57, -2
	s_cmp_lg_u32 s48, 1
	s_cbranch_scc1 .Lpeel_sw
	v_mov_b32_e32 v0, 0
	v_mov_b32_e32 v1, v0
	v_mov_b32_e32 v2, v0
	v_mov_b32_e32 v3, v0
	v_mov_b32_e32 v4, v0
	v_mov_b32_e32 v5, v0
	v_mov_b32_e32 v6, v0
	v_mov_b32_e32 v7, v0
	v_mov_b32_e32 v16, v0
	v_mov_b32_e32 v17, v0
	v_mov_b32_e32 v18, v0
	v_mov_b32_e32 v19, v0
	v_mov_b32_e32 v20, v0
	v_mov_b32_e32 v21, v0
	v_mov_b32_e32 v22, v0
	v_mov_b32_e32 v23, v0
	v_mov_b32_e32 v36, v0
	v_mov_b32_e32 v37, v0
	v_mov_b32_e32 v38, v0
	v_mov_b32_e32 v39, v0
	v_mov_b32_e32 v40, v0
	v_mov_b32_e32 v41, v0
	v_mov_b32_e32 v42, v0
	v_mov_b32_e32 v43, v0
	v_mov_b32_e32 v52, v0
	v_mov_b32_e32 v53, v0
	v_mov_b32_e32 v54, v0
	v_mov_b32_e32 v55, v0
	v_mov_b32_e32 v56, v0
	v_mov_b32_e32 v57, v0
	v_mov_b32_e32 v58, v0
	v_mov_b32_e32 v59, v0
	v_mov_b32_e32 v8, v0
	v_mov_b32_e32 v9, v0
	v_mov_b32_e32 v10, v0
	v_mov_b32_e32 v11, v0
	v_mov_b32_e32 v12, v0
	v_mov_b32_e32 v13, v0
	v_mov_b32_e32 v14, v0
	v_mov_b32_e32 v15, v0
	v_mov_b32_e32 v24, v0
	v_mov_b32_e32 v25, v0
	v_mov_b32_e32 v26, v0
	v_mov_b32_e32 v27, v0
	v_mov_b32_e32 v28, v0
	v_mov_b32_e32 v29, v0
	v_mov_b32_e32 v30, v0
	v_mov_b32_e32 v31, v0
	v_mov_b32_e32 v44, v0
	v_mov_b32_e32 v45, v0
	v_mov_b32_e32 v46, v0
	v_mov_b32_e32 v47, v0
	v_mov_b32_e32 v48, v0
	v_mov_b32_e32 v49, v0
	v_mov_b32_e32 v50, v0
	v_mov_b32_e32 v51, v0
	v_mov_b32_e32 v60, v0
	v_mov_b32_e32 v61, v0
	v_mov_b32_e32 v62, v0
	v_mov_b32_e32 v63, v0
	v_mov_b32_e32 v64, v0
	v_mov_b32_e32 v65, v0
	v_mov_b32_e32 v66, v0
	v_mov_b32_e32 v67, v0
	v_mov_b32_e32 v68, v0
	v_mov_b32_e32 v69, v0
	v_mov_b32_e32 v70, v0
	v_mov_b32_e32 v71, v0
	v_mov_b32_e32 v72, v0
	v_mov_b32_e32 v73, v0
	v_mov_b32_e32 v74, v0
	v_mov_b32_e32 v75, v0
	v_mov_b32_e32 v84, v0
	v_mov_b32_e32 v85, v0
	v_mov_b32_e32 v86, v0
	v_mov_b32_e32 v87, v0
	v_mov_b32_e32 v88, v0
	v_mov_b32_e32 v89, v0
	v_mov_b32_e32 v90, v0
	v_mov_b32_e32 v91, v0
	v_mov_b32_e32 v100, v0
	v_mov_b32_e32 v101, v0
	v_mov_b32_e32 v102, v0
	v_mov_b32_e32 v103, v0
	v_mov_b32_e32 v104, v0
	v_mov_b32_e32 v105, v0
	v_mov_b32_e32 v106, v0
	v_mov_b32_e32 v107, v0
	v_mov_b32_e32 v116, v0
	v_mov_b32_e32 v117, v0
	v_mov_b32_e32 v118, v0
	v_mov_b32_e32 v119, v0
	v_mov_b32_e32 v120, v0
	v_mov_b32_e32 v121, v0
	v_mov_b32_e32 v122, v0
	v_mov_b32_e32 v123, v0
	v_mov_b32_e32 v76, v0
	v_mov_b32_e32 v77, v0
	v_mov_b32_e32 v78, v0
	v_mov_b32_e32 v79, v0
	v_mov_b32_e32 v80, v0
	v_mov_b32_e32 v81, v0
	v_mov_b32_e32 v82, v0
	v_mov_b32_e32 v83, v0
	v_mov_b32_e32 v92, v0
	v_mov_b32_e32 v93, v0
	v_mov_b32_e32 v94, v0
	v_mov_b32_e32 v95, v0
	v_mov_b32_e32 v96, v0
	v_mov_b32_e32 v97, v0
	v_mov_b32_e32 v98, v0
	v_mov_b32_e32 v99, v0
	v_mov_b32_e32 v108, v0
	v_mov_b32_e32 v109, v0
	v_mov_b32_e32 v110, v0
	v_mov_b32_e32 v111, v0
	v_mov_b32_e32 v112, v0
	v_mov_b32_e32 v113, v0
	v_mov_b32_e32 v114, v0
	v_mov_b32_e32 v115, v0
	v_mov_b32_e32 v124, v0
	v_mov_b32_e32 v125, v0
	v_mov_b32_e32 v126, v0
	v_mov_b32_e32 v127, v0
	v_mov_b32_e32 v128, v0
	v_mov_b32_e32 v129, v0
	v_mov_b32_e32 v130, v0
	v_mov_b32_e32 v131, v0

; #define PG8_STAGE(bufoff, gbase, voff) do { _Pragma("unroll") for (int _i = 0; _i < 2; ++_i) \
;         __builtin_amdgcn_global_load_lds((const unsigned*)((const char*)(gbase) + (voff)[_i]), (PG8_LAS unsigned*)(lds + (bufoff) + ldsw + _i * 8192), 16, 0, 0); } while (0)
; #define PG8_LDA(dst, b, h) do { _Pragma("unroll") for (int m = 0; m < 4; ++m) _Pragma("unroll") for (int k = 0; k < 2; ++k) dst[m][k] = *(const PG8_LAS bf16x8*)(lds + PG8_SA(b, h) + aoff + m * 2048 + k * 1024); } while (0)
; #define PG8_LDB(dst, b, h) do { _Pragma("unroll") for (int n = 0; n < 2; ++n) _Pragma("unroll") for (int k = 0; k < 2; ++k) dst[n][k] = *(const PG8_LAS bf16x8*)(lds + PG8_SB(b, h) + boff + n * 2048 + k * 1024); } while (0)
; #define PG8_MMA(ai, bj, At, Bt) do { __builtin_amdgcn_s_setprio(1); _Pragma("unroll") for (int m = 0; m < 4; ++m) _Pragma("unroll") for (int n = 0; n < 2; ++n) _Pragma("unroll") for (int k = 0; k < 2; ++k) \
;         acc[ai][bj][m][n] = __builtin_amdgcn_mfma_f32_16x16x32_bf16(Bt[n][k], At[m][k], acc[ai][bj][m][n], 0, 0, 0); __builtin_amdgcn_s_setprio(0); } while (0)
; #define PG8_WAIT_V(n) asm volatile("s_waitcnt vmcnt(" #n ")" ::: "memory")
; #define PG8_WAIT_L(n) asm volatile("s_waitcnt lgkmcnt(" #n ")" ::: "memory")
; #define PG8_BAR __builtin_amdgcn_s_barrier()
; #define PG8_SCHED __builtin_amdgcn_sched_barrier(0)
; template <class Epi, class Sched, bool ALIGN_EPI = false, bool SP2 = false>
; __device__ __forceinline__ void gemm_phase(PG8_LAS unsigned char* lds, const Gemm g, const Sched& S, const Epi& E) {
;     ...
;             PG8_LDB(B0, 0, 0); PG8_LDB(B1, 0, 1); PG8_SCHED; PG8_LDA(At, 0, 0); PG8_STAGE(PG8_SA(1, 1), a1 + hstep, voffA);
;             PG8_WAIT_V(8); PG8_WAIT_L(0); PG8_BAR; PG8_MMA(0, 0, At, B0); PG8_MMA(0, 1, At, B1); PG8_BAR; PG8_SCHED;
;             PG8_LDA(At, 0, 1); PG8_STAGE(PG8_SB(0, 0), b2, voffB); PG8_STAGE(PG8_SB(0, 1), b2 + hstep, voffB); PG8_STAGE(PG8_SA(0, 0), a2, voffA);
;             PG8_WAIT_V(8); PG8_WAIT_L(0); PG8_BAR; PG8_MMA(1, 0, At, B0); PG8_MMA(1, 1, At, B1); PG8_BAR; PG8_SCHED;
.Lpeel_sw:
	s_add_u32 s22, s0, 0xfffc0080
	s_addc_u32 s23, s1, -1
	s_add_i32 s58, 0, 0x10000
	s_cmp_eq_u32 s57, 12
	s_cselect_b32 s41, s17, s23
	s_cselect_b32 s40, s53, s22
	v_add_u32_e32 v144, s58, v147
	s_cselect_b32 s23, s15, s56
	s_cselect_b32 s22, s54, s55
	s_add_i32 s60, 0, 0x14000
	ds_read_b128 v[140:143], v144
	ds_read_b128 v[150:153], v144 offset:1024
	ds_read_b128 v[154:157], v144 offset:2048
	ds_read_b128 v[158:161], v144 offset:3072
	v_add_u32_e32 v144, s60, v147
	ds_read_b128 v[162:165], v144
	ds_read_b128 v[166:169], v144 offset:1024
	ds_read_b128 v[170:173], v144 offset:2048
	ds_read_b128 v[174:177], v144 offset:3072
	v_lshl_add_u64 v[144:145], s[0:1], 0, v[136:137]
	s_add_i32 m0, s44, 0xc000
	ds_read_b128 v[178:181], v149
	ds_read_b128 v[182:185], v149 offset:1024
	ds_read_b128 v[186:189], v149 offset:2048
	ds_read_b128 v[190:193], v149 offset:3072
	ds_read_b128 v[202:205], v149 offset:4096
	ds_read_b128 v[206:209], v149 offset:5120
	ds_read_b128 v[210:213], v149 offset:6144
	ds_read_b128 v[214:217], v149 offset:7168
	global_load_lds_dwordx4 v[144:145], off
	v_lshl_add_u64 v[144:145], s[0:1], 0, v[138:139]
	s_add_i32 m0, s44, 0xe000
	s_nop 0
	global_load_lds_dwordx4 v[144:145], off
	s_waitcnt vmcnt(16)
	s_waitcnt lgkmcnt(0)
	v_mfma_f32_16x16x32_bf16 v[128:131], v[140:143], v[178:181], 0
	v_mfma_f32_16x16x32_bf16 v[124:127], v[154:157], v[178:181], 0
	v_mfma_f32_16x16x32_bf16 v[112:115], v[140:143], v[186:189], 0
	v_mfma_f32_16x16x32_bf16 v[108:111], v[154:157], v[186:189], 0
	s_barrier
	s_setprio 1
	v_mfma_f32_16x16x32_bf16 v[96:99], v[140:143], v[202:205], 0
	v_mfma_f32_16x16x32_bf16 v[92:95], v[154:157], v[202:205], 0
	v_mfma_f32_16x16x32_bf16 v[80:83], v[140:143], v[210:213], 0
	v_mfma_f32_16x16x32_bf16 v[76:79], v[154:157], v[210:213], 0
	v_mfma_f32_16x16x32_bf16 v[128:131], v[150:153], v[182:185], v[128:131]
	v_mfma_f32_16x16x32_bf16 v[124:127], v[158:161], v[182:185], v[124:127]
	v_mfma_f32_16x16x32_bf16 v[112:115], v[150:153], v[190:193], v[112:115]
	v_mfma_f32_16x16x32_bf16 v[108:111], v[158:161], v[190:193], v[108:111]
	v_mfma_f32_16x16x32_bf16 v[96:99], v[150:153], v[206:209], v[96:99]
	v_mfma_f32_16x16x32_bf16 v[92:95], v[158:161], v[206:209], v[92:95]
	v_mfma_f32_16x16x32_bf16 v[80:83], v[150:153], v[214:217], v[80:83]
	v_mfma_f32_16x16x32_bf16 v[76:79], v[158:161], v[214:217], v[76:79]
	s_setprio 0
	s_setprio 1
	v_mfma_f32_16x16x32_bf16 v[120:123], v[162:165], v[178:181], 0
	v_mfma_f32_16x16x32_bf16 v[116:119], v[170:173], v[178:181], 0
	v_mfma_f32_16x16x32_bf16 v[104:107], v[162:165], v[186:189], 0
	v_mfma_f32_16x16x32_bf16 v[100:103], v[170:173], v[186:189], 0
	v_mfma_f32_16x16x32_bf16 v[88:91], v[162:165], v[202:205], 0
	v_mfma_f32_16x16x32_bf16 v[84:87], v[170:173], v[202:205], 0
	v_mfma_f32_16x16x32_bf16 v[72:75], v[162:165], v[210:213], 0
	v_mfma_f32_16x16x32_bf16 v[68:71], v[170:173], v[210:213], 0
	v_mfma_f32_16x16x32_bf16 v[120:123], v[166:169], v[182:185], v[120:123]
	v_mfma_f32_16x16x32_bf16 v[116:119], v[174:177], v[182:185], v[116:119]
	v_mfma_f32_16x16x32_bf16 v[104:107], v[166:169], v[190:193], v[104:107]
	v_mfma_f32_16x16x32_bf16 v[100:103], v[174:177], v[190:193], v[100:103]
	v_mfma_f32_16x16x32_bf16 v[88:91], v[166:169], v[206:209], v[88:91]
	v_mfma_f32_16x16x32_bf16 v[84:87], v[174:177], v[206:209], v[84:87]
	v_mfma_f32_16x16x32_bf16 v[72:75], v[166:169], v[214:217], v[72:75]
	v_mfma_f32_16x16x32_bf16 v[68:71], v[174:177], v[214:217], v[68:71]
	s_setprio 0
	s_barrier
	s_add_i32 s58, s58, s43
	v_lshl_add_u64 v[144:145], s[22:23], 0, v[196:197]
	s_mov_b32 m0, s58
	ds_read_b128 v[178:181], v149 offset:16384
	ds_read_b128 v[182:185], v149 offset:17408
	ds_read_b128 v[186:189], v149 offset:18432
	ds_read_b128 v[190:193], v149 offset:19456
	ds_read_b128 v[202:205], v149 offset:20480
	ds_read_b128 v[206:209], v149 offset:21504
	ds_read_b128 v[210:213], v149 offset:22528
	ds_read_b128 v[214:217], v149 offset:23552
	global_load_lds_dwordx4 v[144:145], off
	s_add_i32 m0, s58, 0x2000
	s_add_u32 s58, s22, 0x40000
	v_lshl_add_u64 v[194:195], s[22:23], 0, v[32:33]
	s_addc_u32 s59, s23, 0
	s_add_i32 s60, s60, s43
	global_load_lds_dwordx4 v[194:195], off
	v_lshl_add_u64 v[218:219], s[58:59], 0, v[196:197]
	s_mov_b32 m0, s60
	v_lshl_add_u64 v[220:221], s[40:41], 0, v[132:133]
	global_load_lds_dwordx4 v[218:219], off
	v_lshl_add_u64 v[218:219], s[58:59], 0, v[32:33]
	s_add_i32 m0, s60, 0x2000
	s_nop 0
	global_load_lds_dwordx4 v[218:219], off
	v_lshl_add_u64 v[218:219], s[40:41], 0, v[134:135]
	s_mov_b32 m0, s44
	s_nop 0
	global_load_lds_dwordx4 v[218:219], off
	s_mov_b32 m0, s45
	s_nop 0
	global_load_lds_dwordx4 v[220:221], off
	s_waitcnt vmcnt(16)
	s_waitcnt lgkmcnt(0)
	v_mfma_f32_16x16x32_bf16 v[64:67], v[140:143], v[178:181], 0
	v_mfma_f32_16x16x32_bf16 v[60:63], v[154:157], v[178:181], 0
	v_mfma_f32_16x16x32_bf16 v[48:51], v[140:143], v[186:189], 0
	v_mfma_f32_16x16x32_bf16 v[44:47], v[154:157], v[186:189], 0
	s_barrier
; #define PG8_STAGE(bufoff, gbase, voff) do { _Pragma("unroll") for (int _i = 0; _i < 2; ++_i) \
;         __builtin_amdgcn_global_load_lds((const unsigned*)((const char*)(gbase) + (voff)[_i]), (PG8_LAS unsigned*)(lds + (bufoff) + ldsw + _i * 8192), 16, 0, 0); } while (0)
; #define PG8_LDA(dst, b, h) do { _Pragma("unroll") for (int m = 0; m < 4; ++m) _Pragma("unroll") for (int k = 0; k < 2; ++k) dst[m][k] = *(const PG8_LAS bf16x8*)(lds + PG8_SA(b, h) + aoff + m * 2048 + k * 1024); } while (0)
; #define PG8_LDB(dst, b, h) do { _Pragma("unroll") for (int n = 0; n < 2; ++n) _Pragma("unroll") for (int k = 0; k < 2; ++k) dst[n][k] = *(const PG8_LAS bf16x8*)(lds + PG8_SB(b, h) + boff + n * 2048 + k * 1024); } while (0)
; #define PG8_MMA(ai, bj, At, Bt) do { __builtin_amdgcn_s_setprio(1); _Pragma("unroll") for (int m = 0; m < 4; ++m) _Pragma("unroll") for (int n = 0; n < 2; ++n) _Pragma("unroll") for (int k = 0; k < 2; ++k) \
;         acc[ai][bj][m][n] = __builtin_amdgcn_mfma_f32_16x16x32_bf16(Bt[n][k], At[m][k], acc[ai][bj][m][n], 0, 0, 0); __builtin_amdgcn_s_setprio(0); } while (0)
; #define PG8_WAIT_V(n) asm volatile("s_waitcnt vmcnt(" #n ")" ::: "memory")
; #define PG8_WAIT_L(n) asm volatile("s_waitcnt lgkmcnt(" #n ")" ::: "memory")
; #define PG8_BAR __builtin_amdgcn_s_barrier()
; #define PG8_SCHED __builtin_amdgcn_sched_barrier(0)
; template <class Epi, class Sched, bool ALIGN_EPI = false, bool SP2 = false>
; __device__ __forceinline__ void gemm_phase(PG8_LAS unsigned char* lds, const Gemm g, const Sched& S, const Epi& E) {
;     ...
;             PG8_WAIT_V(8); PG8_WAIT_L(0); PG8_BAR; PG8_MMA(1, 0, At, B0); PG8_MMA(1, 1, At, B1); PG8_BAR; PG8_SCHED;
;             PG8_LDB(B0, 1, 0); PG8_LDB(B1, 1, 1); PG8_SCHED; PG8_LDA(At, 1, 0); PG8_STAGE(PG8_SA(0, 1), a2 + hstep, voffA);
;             PG8_WAIT_V(8); PG8_WAIT_L(0); PG8_BAR; PG8_MMA(0, 0, At, B0); PG8_MMA(0, 1, At, B1); PG8_BAR; PG8_SCHED;
	s_setprio 1
	v_mfma_f32_16x16x32_bf16 v[28:31], v[140:143], v[202:205], 0
	v_mfma_f32_16x16x32_bf16 v[24:27], v[154:157], v[202:205], 0
	v_mfma_f32_16x16x32_bf16 v[12:15], v[140:143], v[210:213], 0
	v_mfma_f32_16x16x32_bf16 v[8:11], v[154:157], v[210:213], 0
	v_mfma_f32_16x16x32_bf16 v[64:67], v[150:153], v[182:185], v[64:67]
	v_mfma_f32_16x16x32_bf16 v[60:63], v[158:161], v[182:185], v[60:63]
	v_mfma_f32_16x16x32_bf16 v[48:51], v[150:153], v[190:193], v[48:51]
	v_mfma_f32_16x16x32_bf16 v[44:47], v[158:161], v[190:193], v[44:47]
	v_mfma_f32_16x16x32_bf16 v[28:31], v[150:153], v[206:209], v[28:31]
	v_mfma_f32_16x16x32_bf16 v[24:27], v[158:161], v[206:209], v[24:27]
	v_mfma_f32_16x16x32_bf16 v[12:15], v[150:153], v[214:217], v[12:15]
	v_mfma_f32_16x16x32_bf16 v[8:11], v[158:161], v[214:217], v[8:11]
	s_setprio 0
	s_setprio 1
	v_mfma_f32_16x16x32_bf16 v[56:59], v[162:165], v[178:181], 0
	v_mfma_f32_16x16x32_bf16 v[52:55], v[170:173], v[178:181], 0
	v_mfma_f32_16x16x32_bf16 v[40:43], v[162:165], v[186:189], 0
	v_mfma_f32_16x16x32_bf16 v[36:39], v[170:173], v[186:189], 0
	v_mfma_f32_16x16x32_bf16 v[20:23], v[162:165], v[202:205], 0
	v_mfma_f32_16x16x32_bf16 v[16:19], v[170:173], v[202:205], 0
	v_mfma_f32_16x16x32_bf16 v[4:7], v[162:165], v[210:213], 0
	v_mfma_f32_16x16x32_bf16 v[0:3], v[170:173], v[210:213], 0
	v_mfma_f32_16x16x32_bf16 v[56:59], v[166:169], v[182:185], v[56:59]
	v_mfma_f32_16x16x32_bf16 v[52:55], v[174:177], v[182:185], v[52:55]
	v_mfma_f32_16x16x32_bf16 v[40:43], v[166:169], v[190:193], v[40:43]
	v_mfma_f32_16x16x32_bf16 v[36:39], v[174:177], v[190:193], v[36:39]
	v_mfma_f32_16x16x32_bf16 v[20:23], v[166:169], v[206:209], v[20:23]
	v_mfma_f32_16x16x32_bf16 v[16:19], v[174:177], v[206:209], v[16:19]
	v_mfma_f32_16x16x32_bf16 v[4:7], v[166:169], v[214:217], v[4:7]
	v_mfma_f32_16x16x32_bf16 v[0:3], v[174:177], v[214:217], v[0:3]
	s_setprio 0
	s_barrier
	s_add_i32 s58, 0, 0x18000
	v_add_u32_e32 v146, s58, v147
	s_add_i32 s59, 0, 0x1c000
	ds_read_b128 v[140:143], v146
	ds_read_b128 v[150:153], v146 offset:1024
	ds_read_b128 v[154:157], v146 offset:2048
	ds_read_b128 v[158:161], v146 offset:3072
	v_add_u32_e32 v146, s59, v147
	ds_read_b128 v[162:165], v146
	ds_read_b128 v[166:169], v146 offset:1024
	ds_read_b128 v[170:173], v146 offset:2048
	ds_read_b128 v[174:177], v146 offset:3072
	s_add_u32 s40, s40, 0x40000
	s_addc_u32 s41, s41, 0
	s_mov_b32 m0, s46
	v_lshl_add_u64 v[222:223], s[40:41], 0, v[134:135]
	ds_read_b128 v[178:181], v149 offset:32768
	ds_read_b128 v[182:185], v149 offset:33792
	ds_read_b128 v[186:189], v149 offset:34816
	ds_read_b128 v[190:193], v149 offset:35840
	ds_read_b128 v[202:205], v149 offset:36864
	ds_read_b128 v[206:209], v149 offset:37888
	ds_read_b128 v[210:213], v149 offset:38912
	ds_read_b128 v[214:217], v149 offset:39936
	global_load_lds_dwordx4 v[222:223], off
	v_lshl_add_u64 v[222:223], s[40:41], 0, v[132:133]
	s_mov_b32 m0, s47
	s_nop 0
	global_load_lds_dwordx4 v[222:223], off
	s_waitcnt vmcnt(8)
	s_waitcnt lgkmcnt(0)
	v_mfma_f32_16x16x32_bf16 v[128:131], v[140:143], v[178:181], v[128:131]
	v_mfma_f32_16x16x32_bf16 v[124:127], v[154:157], v[178:181], v[124:127]
	v_mfma_f32_16x16x32_bf16 v[112:115], v[140:143], v[186:189], v[112:115]
	v_mfma_f32_16x16x32_bf16 v[108:111], v[154:157], v[186:189], v[108:111]
	s_barrier
	s_setprio 1
	v_mfma_f32_16x16x32_bf16 v[96:99], v[140:143], v[202:205], v[96:99]
	v_mfma_f32_16x16x32_bf16 v[92:95], v[154:157], v[202:205], v[92:95]
	v_mfma_f32_16x16x32_bf16 v[80:83], v[140:143], v[210:213], v[80:83]
	v_mfma_f32_16x16x32_bf16 v[76:79], v[154:157], v[210:213], v[76:79]
	v_mfma_f32_16x16x32_bf16 v[128:131], v[150:153], v[182:185], v[128:131]
	v_mfma_f32_16x16x32_bf16 v[124:127], v[158:161], v[182:185], v[124:127]
	v_mfma_f32_16x16x32_bf16 v[112:115], v[150:153], v[190:193], v[112:115]
	v_mfma_f32_16x16x32_bf16 v[108:111], v[158:161], v[190:193], v[108:111]
	v_mfma_f32_16x16x32_bf16 v[96:99], v[150:153], v[206:209], v[96:99]
	v_mfma_f32_16x16x32_bf16 v[92:95], v[158:161], v[206:209], v[92:95]
	v_mfma_f32_16x16x32_bf16 v[80:83], v[150:153], v[214:217], v[80:83]
	v_mfma_f32_16x16x32_bf16 v[76:79], v[158:161], v[214:217], v[76:79]
	s_setprio 0
	s_setprio 1
	v_mfma_f32_16x16x32_bf16 v[120:123], v[162:165], v[178:181], v[120:123]
	v_mfma_f32_16x16x32_bf16 v[116:119], v[170:173], v[178:181], v[116:119]
	v_mfma_f32_16x16x32_bf16 v[104:107], v[162:165], v[186:189], v[104:107]
	v_mfma_f32_16x16x32_bf16 v[100:103], v[170:173], v[186:189], v[100:103]
	v_mfma_f32_16x16x32_bf16 v[88:91], v[162:165], v[202:205], v[88:91]
	v_mfma_f32_16x16x32_bf16 v[84:87], v[170:173], v[202:205], v[84:87]
	v_mfma_f32_16x16x32_bf16 v[72:75], v[162:165], v[210:213], v[72:75]
	v_mfma_f32_16x16x32_bf16 v[68:71], v[170:173], v[210:213], v[68:71]
	v_mfma_f32_16x16x32_bf16 v[120:123], v[166:169], v[182:185], v[120:123]
	v_mfma_f32_16x16x32_bf16 v[116:119], v[174:177], v[182:185], v[116:119]
	v_mfma_f32_16x16x32_bf16 v[104:107], v[166:169], v[190:193], v[104:107]
	v_mfma_f32_16x16x32_bf16 v[100:103], v[174:177], v[190:193], v[100:103]
	v_mfma_f32_16x16x32_bf16 v[88:91], v[166:169], v[206:209], v[88:91]
	v_mfma_f32_16x16x32_bf16 v[84:87], v[174:177], v[206:209], v[84:87]
	v_mfma_f32_16x16x32_bf16 v[72:75], v[166:169], v[214:217], v[72:75]
	v_mfma_f32_16x16x32_bf16 v[68:71], v[174:177], v[214:217], v[68:71]
	s_setprio 0
	s_barrier
; #define PG8_STAGE(bufoff, gbase, voff) do { _Pragma("unroll") for (int _i = 0; _i < 2; ++_i) \
;         __builtin_amdgcn_global_load_lds((const unsigned*)((const char*)(gbase) + (voff)[_i]), (PG8_LAS unsigned*)(lds + (bufoff) + ldsw + _i * 8192), 16, 0, 0); } while (0)
; #define PG8_LDA(dst, b, h) do { _Pragma("unroll") for (int m = 0; m < 4; ++m) _Pragma("unroll") for (int k = 0; k < 2; ++k) dst[m][k] = *(const PG8_LAS bf16x8*)(lds + PG8_SA(b, h) + aoff + m * 2048 + k * 1024); } while (0)
; #define PG8_LDB(dst, b, h) do { _Pragma("unroll") for (int n = 0; n < 2; ++n) _Pragma("unroll") for (int k = 0; k < 2; ++k) dst[n][k] = *(const PG8_LAS bf16x8*)(lds + PG8_SB(b, h) + boff + n * 2048 + k * 1024); } while (0)
; #define PG8_MMA(ai, bj, At, Bt) do { __builtin_amdgcn_s_setprio(1); _Pragma("unroll") for (int m = 0; m < 4; ++m) _Pragma("unroll") for (int n = 0; n < 2; ++n) _Pragma("unroll") for (int k = 0; k < 2; ++k) \
;         acc[ai][bj][m][n] = __builtin_amdgcn_mfma_f32_16x16x32_bf16(Bt[n][k], At[m][k], acc[ai][bj][m][n], 0, 0, 0); __builtin_amdgcn_s_setprio(0); } while (0)
; #define PG8_WAIT_V(n) asm volatile("s_waitcnt vmcnt(" #n ")" ::: "memory")
; #define PG8_WAIT_L(n) asm volatile("s_waitcnt lgkmcnt(" #n ")" ::: "memory")
; #define PG8_BAR __builtin_amdgcn_s_barrier()
; #define PG8_SCHED __builtin_amdgcn_sched_barrier(0)
; template <class Epi, class Sched, bool ALIGN_EPI = false, bool SP2 = false>
; __device__ __forceinline__ void gemm_phase(PG8_LAS unsigned char* lds, const Gemm g, const Sched& S, const Epi& E) {
;     ...
;             PG8_LDB(B0, 0, 0); PG8_LDB(B1, 0, 1); PG8_SCHED; PG8_LDA(At, 0, 0); PG8_STAGE(PG8_SA(1, 1), a1 + hstep, voffA);
;             PG8_WAIT_V(8); PG8_WAIT_L(0); PG8_BAR; PG8_MMA(0, 0, At, B0); PG8_MMA(0, 1, At, B1); PG8_BAR; PG8_SCHED;
;     ...
;             PG8_LDA(At, 1, 1); PG8_STAGE(PG8_SB(1, 0), b3, voffB); PG8_STAGE(PG8_SB(1, 1), b3 + hstep, voffB); PG8_STAGE(PG8_SA(1, 0), a3, voffA);
;             PG8_WAIT_V(8); PG8_WAIT_L(0); PG8_BAR; PG8_MMA(1, 0, At, B0); PG8_MMA(1, 1, At, B1); PG8_BAR; PG8_SCHED;
	s_add_i32 s40, s58, s43
	v_lshl_add_u64 v[144:145], v[144:145], 0, s[36:37]
	s_mov_b32 m0, s40
	ds_read_b128 v[178:181], v149 offset:49152
	ds_read_b128 v[182:185], v149 offset:50176
	ds_read_b128 v[186:189], v149 offset:51200
	ds_read_b128 v[190:193], v149 offset:52224
	ds_read_b128 v[202:205], v149 offset:53248
	ds_read_b128 v[206:209], v149 offset:54272
	ds_read_b128 v[210:213], v149 offset:55296
	ds_read_b128 v[214:217], v149 offset:56320
	global_load_lds_dwordx4 v[144:145], off
	s_add_i32 m0, s40, 0x2000
	s_add_u32 s22, s22, 0x40080
	v_lshl_add_u64 v[144:145], v[194:195], 0, s[36:37]
	s_addc_u32 s23, s23, 0
	s_add_i32 s40, s59, s43
	global_load_lds_dwordx4 v[144:145], off
	v_lshl_add_u64 v[144:145], s[22:23], 0, v[196:197]
	s_mov_b32 m0, s40
	s_nop 0
	global_load_lds_dwordx4 v[144:145], off
	v_lshl_add_u64 v[144:145], s[22:23], 0, v[32:33]
	s_add_i32 m0, s40, 0x2000
	s_nop 0
	global_load_lds_dwordx4 v[144:145], off
	v_lshl_add_u64 v[144:145], v[218:219], 0, s[36:37]
	s_mov_b32 m0, s49
	s_nop 0
	global_load_lds_dwordx4 v[144:145], off
	v_lshl_add_u64 v[144:145], v[220:221], 0, s[36:37]
	s_mov_b32 m0, s50
	s_nop 0
	global_load_lds_dwordx4 v[144:145], off
	s_waitcnt vmcnt(8)
	s_waitcnt lgkmcnt(0)
	v_mfma_f32_16x16x32_bf16 v[64:67], v[140:143], v[178:181], v[64:67]
	v_mfma_f32_16x16x32_bf16 v[60:63], v[154:157], v[178:181], v[60:63]
	v_mfma_f32_16x16x32_bf16 v[48:51], v[140:143], v[186:189], v[48:51]
	v_mfma_f32_16x16x32_bf16 v[44:47], v[154:157], v[186:189], v[44:47]
	s_barrier
	s_setprio 1
	v_mfma_f32_16x16x32_bf16 v[28:31], v[140:143], v[202:205], v[28:31]
	v_mfma_f32_16x16x32_bf16 v[24:27], v[154:157], v[202:205], v[24:27]
	v_mfma_f32_16x16x32_bf16 v[12:15], v[140:143], v[210:213], v[12:15]
	v_mfma_f32_16x16x32_bf16 v[8:11], v[154:157], v[210:213], v[8:11]
	v_mfma_f32_16x16x32_bf16 v[64:67], v[150:153], v[182:185], v[64:67]
	v_mfma_f32_16x16x32_bf16 v[60:63], v[158:161], v[182:185], v[60:63]
	v_mfma_f32_16x16x32_bf16 v[48:51], v[150:153], v[190:193], v[48:51]
	v_mfma_f32_16x16x32_bf16 v[44:47], v[158:161], v[190:193], v[44:47]
	v_mfma_f32_16x16x32_bf16 v[28:31], v[150:153], v[206:209], v[28:31]
	v_mfma_f32_16x16x32_bf16 v[24:27], v[158:161], v[206:209], v[24:27]
	v_mfma_f32_16x16x32_bf16 v[12:15], v[150:153], v[214:217], v[12:15]
	v_mfma_f32_16x16x32_bf16 v[8:11], v[158:161], v[214:217], v[8:11]
	s_setprio 0
	s_setprio 1
	v_mfma_f32_16x16x32_bf16 v[56:59], v[162:165], v[178:181], v[56:59]
	v_mfma_f32_16x16x32_bf16 v[52:55], v[170:173], v[178:181], v[52:55]
	v_mfma_f32_16x16x32_bf16 v[40:43], v[162:165], v[186:189], v[40:43]
	v_mfma_f32_16x16x32_bf16 v[36:39], v[170:173], v[186:189], v[36:39]
	v_mfma_f32_16x16x32_bf16 v[20:23], v[162:165], v[202:205], v[20:23]
	v_mfma_f32_16x16x32_bf16 v[16:19], v[170:173], v[202:205], v[16:19]
	v_mfma_f32_16x16x32_bf16 v[4:7], v[162:165], v[210:213], v[4:7]
	v_mfma_f32_16x16x32_bf16 v[0:3], v[170:173], v[210:213], v[0:3]
	v_mfma_f32_16x16x32_bf16 v[56:59], v[166:169], v[182:185], v[56:59]
	v_mfma_f32_16x16x32_bf16 v[52:55], v[174:177], v[182:185], v[52:55]
	v_mfma_f32_16x16x32_bf16 v[40:43], v[166:169], v[190:193], v[40:43]
	v_mfma_f32_16x16x32_bf16 v[36:39], v[174:177], v[190:193], v[36:39]
	v_mfma_f32_16x16x32_bf16 v[20:23], v[166:169], v[206:209], v[20:23]
	v_mfma_f32_16x16x32_bf16 v[16:19], v[174:177], v[206:209], v[16:19]
	v_mfma_f32_16x16x32_bf16 v[4:7], v[166:169], v[214:217], v[4:7]
	v_mfma_f32_16x16x32_bf16 v[0:3], v[174:177], v[214:217], v[0:3]
	s_setprio 0
	s_barrier
	s_add_i32 s57, s57, 2
	s_add_u32 s0, s0, 0x100
	s_addc_u32 s1, s1, 0
	s_add_u32 s55, s55, 0x100
	s_addc_u32 s56, s56, 0
	s_cmp_gt_u32 s57, 13
	s_branch .LBB0_623
.Lpeel_pg:
	s_add_u32 s4, s0, 0xfffc0080
	s_addc_u32 s5, s1, -1
	s_add_i32 s60, 0, 0x10000
	s_cmp_eq_u32 s59, 12
	s_cselect_b32 s43, s21, s5
	s_cselect_b32 s42, s45, s4
	s_cselect_b32 s5, s19, s58
	s_cselect_b32 s4, s46, s47
	s_add_i32 s62, 0, 0x14000
	v_add_u32_e32 v144, s60, v170
	v_add_u32_e32 v174, s62, v170
	ds_read_b128 v[132:135], v144
	ds_read_b128 v[136:139], v144 offset:1024
	ds_read_b128 v[140:143], v144 offset:2048
	ds_read_b128 v[144:147], v144 offset:3072
	ds_read_b128 v[158:161], v174
	ds_read_b128 v[162:165], v174 offset:1024
	ds_read_b128 v[166:169], v174 offset:2048
	ds_read_b128 v[174:177], v174 offset:3072
	v_lshl_add_u64 v[194:195], s[0:1], 0, v[154:155]
	s_add_i32 m0, s50, 0xc000
	ds_read_b128 v[178:181], v173
	ds_read_b128 v[182:185], v173 offset:1024
	ds_read_b128 v[186:189], v173 offset:2048
	ds_read_b128 v[190:193], v173 offset:3072
	ds_read_b128 v[202:205], v173 offset:4096
	ds_read_b128 v[206:209], v173 offset:5120
	ds_read_b128 v[210:213], v173 offset:6144
	ds_read_b128 v[214:217], v173 offset:7168
	global_load_lds_dwordx4 v[194:195], off
	v_lshl_add_u64 v[194:195], s[0:1], 0, v[156:157]
	s_add_i32 m0, s50, 0xe000
	s_nop 0
	global_load_lds_dwordx4 v[194:195], off
	s_waitcnt vmcnt(16)
	s_waitcnt lgkmcnt(0)
	v_mfma_f32_16x16x32_bf16 v[128:131], v[132:135], v[178:181], 0
	v_mfma_f32_16x16x32_bf16 v[124:127], v[140:143], v[178:181], 0
	v_mfma_f32_16x16x32_bf16 v[112:115], v[132:135], v[186:189], 0
	v_mfma_f32_16x16x32_bf16 v[108:111], v[140:143], v[186:189], 0
	s_barrier
; #define PG8_STAGE(bufoff, gbase, voff) do { _Pragma("unroll") for (int _i = 0; _i < 2; ++_i) \
;         __builtin_amdgcn_global_load_lds((const unsigned*)((const char*)(gbase) + (voff)[_i]), (PG8_LAS unsigned*)(lds + (bufoff) + ldsw + _i * 8192), 16, 0, 0); } while (0)
; #define PG8_LDA(dst, b, h) do { _Pragma("unroll") for (int m = 0; m < 4; ++m) _Pragma("unroll") for (int k = 0; k < 2; ++k) dst[m][k] = *(const PG8_LAS bf16x8*)(lds + PG8_SA(b, h) + aoff + m * 2048 + k * 1024); } while (0)
; #define PG8_MMA(ai, bj, At, Bt) do { __builtin_amdgcn_s_setprio(1); _Pragma("unroll") for (int m = 0; m < 4; ++m) _Pragma("unroll") for (int n = 0; n < 2; ++n) _Pragma("unroll") for (int k = 0; k < 2; ++k) \
;         acc[ai][bj][m][n] = __builtin_amdgcn_mfma_f32_16x16x32_bf16(Bt[n][k], At[m][k], acc[ai][bj][m][n], 0, 0, 0); __builtin_amdgcn_s_setprio(0); } while (0)
; #define PG8_WAIT_V(n) asm volatile("s_waitcnt vmcnt(" #n ")" ::: "memory")
; #define PG8_WAIT_L(n) asm volatile("s_waitcnt lgkmcnt(" #n ")" ::: "memory")
; #define PG8_BAR __builtin_amdgcn_s_barrier()
; #define PG8_SCHED __builtin_amdgcn_sched_barrier(0)
; template <class Epi, class Sched, bool ALIGN_EPI = false, bool SP2 = false>
; __device__ __forceinline__ void gemm_phase(PG8_LAS unsigned char* lds, const Gemm g, const Sched& S, const Epi& E) {
;     ...
;             PG8_WAIT_V(8); PG8_WAIT_L(0); PG8_BAR; PG8_MMA(0, 0, At, B0); PG8_MMA(0, 1, At, B1); PG8_BAR; PG8_SCHED;
;             PG8_LDA(At, 0, 1); PG8_STAGE(PG8_SB(0, 0), b2, voffB); PG8_STAGE(PG8_SB(0, 1), b2 + hstep, voffB); PG8_STAGE(PG8_SA(0, 0), a2, voffA);
;             PG8_WAIT_V(8); PG8_WAIT_L(0); PG8_BAR; PG8_MMA(1, 0, At, B0); PG8_MMA(1, 1, At, B1); PG8_BAR; PG8_SCHED;
	s_setprio 1
	v_mfma_f32_16x16x32_bf16 v[96:99], v[132:135], v[202:205], 0
	v_mfma_f32_16x16x32_bf16 v[92:95], v[140:143], v[202:205], 0
	v_mfma_f32_16x16x32_bf16 v[80:83], v[132:135], v[210:213], 0
	v_mfma_f32_16x16x32_bf16 v[76:79], v[140:143], v[210:213], 0
	v_mfma_f32_16x16x32_bf16 v[128:131], v[136:139], v[182:185], v[128:131]
	v_mfma_f32_16x16x32_bf16 v[124:127], v[144:147], v[182:185], v[124:127]
	v_mfma_f32_16x16x32_bf16 v[112:115], v[136:139], v[190:193], v[112:115]
	v_mfma_f32_16x16x32_bf16 v[108:111], v[144:147], v[190:193], v[108:111]
	v_mfma_f32_16x16x32_bf16 v[96:99], v[136:139], v[206:209], v[96:99]
	v_mfma_f32_16x16x32_bf16 v[92:95], v[144:147], v[206:209], v[92:95]
	v_mfma_f32_16x16x32_bf16 v[80:83], v[136:139], v[214:217], v[80:83]
	v_mfma_f32_16x16x32_bf16 v[76:79], v[144:147], v[214:217], v[76:79]
	s_setprio 0
	s_setprio 1
	v_mfma_f32_16x16x32_bf16 v[120:123], v[158:161], v[178:181], 0
	v_mfma_f32_16x16x32_bf16 v[116:119], v[166:169], v[178:181], 0
	v_mfma_f32_16x16x32_bf16 v[104:107], v[158:161], v[186:189], 0
	v_mfma_f32_16x16x32_bf16 v[100:103], v[166:169], v[186:189], 0
	v_mfma_f32_16x16x32_bf16 v[88:91], v[158:161], v[202:205], 0
	v_mfma_f32_16x16x32_bf16 v[84:87], v[166:169], v[202:205], 0
	v_mfma_f32_16x16x32_bf16 v[72:75], v[158:161], v[210:213], 0
	v_mfma_f32_16x16x32_bf16 v[68:71], v[166:169], v[210:213], 0
	v_mfma_f32_16x16x32_bf16 v[120:123], v[162:165], v[182:185], v[120:123]
	v_mfma_f32_16x16x32_bf16 v[116:119], v[174:177], v[182:185], v[116:119]
	v_mfma_f32_16x16x32_bf16 v[104:107], v[162:165], v[190:193], v[104:107]
	v_mfma_f32_16x16x32_bf16 v[100:103], v[174:177], v[190:193], v[100:103]
	v_mfma_f32_16x16x32_bf16 v[88:91], v[162:165], v[206:209], v[88:91]
	v_mfma_f32_16x16x32_bf16 v[84:87], v[174:177], v[206:209], v[84:87]
	v_mfma_f32_16x16x32_bf16 v[72:75], v[162:165], v[214:217], v[72:75]
	v_mfma_f32_16x16x32_bf16 v[68:71], v[174:177], v[214:217], v[68:71]
	s_setprio 0
	s_barrier
	s_add_i32 s60, s60, s49
	v_lshl_add_u64 v[194:195], s[4:5], 0, v[150:151]
	s_mov_b32 m0, s60
	ds_read_b128 v[178:181], v173 offset:16384
	ds_read_b128 v[182:185], v173 offset:17408
	ds_read_b128 v[186:189], v173 offset:18432
	ds_read_b128 v[190:193], v173 offset:19456
	ds_read_b128 v[202:205], v173 offset:20480
	ds_read_b128 v[206:209], v173 offset:21504
	ds_read_b128 v[210:213], v173 offset:22528
	ds_read_b128 v[214:217], v173 offset:23552
	global_load_lds_dwordx4 v[194:195], off
	s_add_i32 m0, s60, 0x2000
	s_add_u32 s60, s4, 0x40000
	v_lshl_add_u64 v[218:219], s[4:5], 0, v[32:33]
	s_addc_u32 s61, s5, 0
	s_add_i32 s62, s62, s49
	global_load_lds_dwordx4 v[218:219], off
	v_lshl_add_u64 v[220:221], s[60:61], 0, v[150:151]
	s_mov_b32 m0, s62
	v_lshl_add_u64 v[222:223], s[42:43], 0, v[148:149]
	global_load_lds_dwordx4 v[220:221], off
	v_lshl_add_u64 v[220:221], s[60:61], 0, v[32:33]
	s_add_i32 m0, s62, 0x2000
	s_nop 0
	global_load_lds_dwordx4 v[220:221], off
	v_lshl_add_u64 v[220:221], s[42:43], 0, v[152:153]
	s_mov_b32 m0, s50
	s_nop 0
	global_load_lds_dwordx4 v[220:221], off
	s_mov_b32 m0, s51
	s_nop 0
	global_load_lds_dwordx4 v[222:223], off
	s_waitcnt vmcnt(16)
	s_waitcnt lgkmcnt(0)
	v_mfma_f32_16x16x32_bf16 v[64:67], v[132:135], v[178:181], 0
	v_mfma_f32_16x16x32_bf16 v[60:63], v[140:143], v[178:181], 0
	v_mfma_f32_16x16x32_bf16 v[48:51], v[132:135], v[186:189], 0
	v_mfma_f32_16x16x32_bf16 v[44:47], v[140:143], v[186:189], 0
	s_barrier
	s_setprio 1
	v_mfma_f32_16x16x32_bf16 v[28:31], v[132:135], v[202:205], 0
	v_mfma_f32_16x16x32_bf16 v[24:27], v[140:143], v[202:205], 0
	v_mfma_f32_16x16x32_bf16 v[12:15], v[132:135], v[210:213], 0
	v_mfma_f32_16x16x32_bf16 v[8:11], v[140:143], v[210:213], 0
	v_mfma_f32_16x16x32_bf16 v[64:67], v[136:139], v[182:185], v[64:67]
	v_mfma_f32_16x16x32_bf16 v[60:63], v[144:147], v[182:185], v[60:63]
	v_mfma_f32_16x16x32_bf16 v[48:51], v[136:139], v[190:193], v[48:51]
	v_mfma_f32_16x16x32_bf16 v[44:47], v[144:147], v[190:193], v[44:47]
	v_mfma_f32_16x16x32_bf16 v[28:31], v[136:139], v[206:209], v[28:31]
	v_mfma_f32_16x16x32_bf16 v[24:27], v[144:147], v[206:209], v[24:27]
	v_mfma_f32_16x16x32_bf16 v[12:15], v[136:139], v[214:217], v[12:15]
	v_mfma_f32_16x16x32_bf16 v[8:11], v[144:147], v[214:217], v[8:11]
	s_setprio 0
	s_setprio 1
	v_mfma_f32_16x16x32_bf16 v[56:59], v[158:161], v[178:181], 0
	v_mfma_f32_16x16x32_bf16 v[52:55], v[166:169], v[178:181], 0
	v_mfma_f32_16x16x32_bf16 v[40:43], v[158:161], v[186:189], 0
	v_mfma_f32_16x16x32_bf16 v[36:39], v[166:169], v[186:189], 0
	v_mfma_f32_16x16x32_bf16 v[20:23], v[158:161], v[202:205], 0
	v_mfma_f32_16x16x32_bf16 v[16:19], v[166:169], v[202:205], 0
	v_mfma_f32_16x16x32_bf16 v[4:7], v[158:161], v[210:213], 0
	v_mfma_f32_16x16x32_bf16 v[0:3], v[166:169], v[210:213], 0
	v_mfma_f32_16x16x32_bf16 v[56:59], v[162:165], v[182:185], v[56:59]
	v_mfma_f32_16x16x32_bf16 v[52:55], v[174:177], v[182:185], v[52:55]
	v_mfma_f32_16x16x32_bf16 v[40:43], v[162:165], v[190:193], v[40:43]
	v_mfma_f32_16x16x32_bf16 v[36:39], v[174:177], v[190:193], v[36:39]
	v_mfma_f32_16x16x32_bf16 v[20:23], v[162:165], v[206:209], v[20:23]
	v_mfma_f32_16x16x32_bf16 v[16:19], v[174:177], v[206:209], v[16:19]
	v_mfma_f32_16x16x32_bf16 v[4:7], v[162:165], v[214:217], v[4:7]
	v_mfma_f32_16x16x32_bf16 v[0:3], v[174:177], v[214:217], v[0:3]
	s_setprio 0
	s_barrier
; #define PG8_STAGE(bufoff, gbase, voff) do { _Pragma("unroll") for (int _i = 0; _i < 2; ++_i) \
;         __builtin_amdgcn_global_load_lds((const unsigned*)((const char*)(gbase) + (voff)[_i]), (PG8_LAS unsigned*)(lds + (bufoff) + ldsw + _i * 8192), 16, 0, 0); } while (0)
; #define PG8_LDA(dst, b, h) do { _Pragma("unroll") for (int m = 0; m < 4; ++m) _Pragma("unroll") for (int k = 0; k < 2; ++k) dst[m][k] = *(const PG8_LAS bf16x8*)(lds + PG8_SA(b, h) + aoff + m * 2048 + k * 1024); } while (0)
; #define PG8_LDB(dst, b, h) do { _Pragma("unroll") for (int n = 0; n < 2; ++n) _Pragma("unroll") for (int k = 0; k < 2; ++k) dst[n][k] = *(const PG8_LAS bf16x8*)(lds + PG8_SB(b, h) + boff + n * 2048 + k * 1024); } while (0)
; #define PG8_MMA(ai, bj, At, Bt) do { __builtin_amdgcn_s_setprio(1); _Pragma("unroll") for (int m = 0; m < 4; ++m) _Pragma("unroll") for (int n = 0; n < 2; ++n) _Pragma("unroll") for (int k = 0; k < 2; ++k) \
;         acc[ai][bj][m][n] = __builtin_amdgcn_mfma_f32_16x16x32_bf16(Bt[n][k], At[m][k], acc[ai][bj][m][n], 0, 0, 0); __builtin_amdgcn_s_setprio(0); } while (0)
; #define PG8_WAIT_V(n) asm volatile("s_waitcnt vmcnt(" #n ")" ::: "memory")
; #define PG8_WAIT_L(n) asm volatile("s_waitcnt lgkmcnt(" #n ")" ::: "memory")
; #define PG8_BAR __builtin_amdgcn_s_barrier()
; #define PG8_SCHED __builtin_amdgcn_sched_barrier(0)
; template <class Epi, class Sched, bool ALIGN_EPI = false, bool SP2 = false>
; __device__ __forceinline__ void gemm_phase(PG8_LAS unsigned char* lds, const Gemm g, const Sched& S, const Epi& E) {
;     ...
;             PG8_LDB(B0, 1, 0); PG8_LDB(B1, 1, 1); PG8_SCHED; PG8_LDA(At, 1, 0); PG8_STAGE(PG8_SA(0, 1), a2 + hstep, voffA);
;             PG8_WAIT_V(8); PG8_WAIT_L(0); PG8_BAR; PG8_MMA(0, 0, At, B0); PG8_MMA(0, 1, At, B1); PG8_BAR; PG8_SCHED;
	s_add_i32 s60, 0, 0x18000
	s_add_i32 s61, 0, 0x1c000
	v_add_u32_e32 v144, s60, v170
	v_add_u32_e32 v174, s61, v170
	ds_read_b128 v[132:135], v144
	ds_read_b128 v[136:139], v144 offset:1024
	ds_read_b128 v[140:143], v144 offset:2048
	ds_read_b128 v[144:147], v144 offset:3072
	ds_read_b128 v[158:161], v174
	ds_read_b128 v[162:165], v174 offset:1024
	ds_read_b128 v[166:169], v174 offset:2048
	ds_read_b128 v[174:177], v174 offset:3072
	s_add_u32 s42, s42, 0x40000
	s_addc_u32 s43, s43, 0
	s_mov_b32 m0, s52
	v_lshl_add_u64 v[224:225], s[42:43], 0, v[152:153]
	ds_read_b128 v[178:181], v173 offset:32768
	ds_read_b128 v[182:185], v173 offset:33792
	ds_read_b128 v[186:189], v173 offset:34816
	ds_read_b128 v[190:193], v173 offset:35840
	ds_read_b128 v[202:205], v173 offset:36864
	ds_read_b128 v[206:209], v173 offset:37888
	ds_read_b128 v[210:213], v173 offset:38912
	ds_read_b128 v[214:217], v173 offset:39936
	global_load_lds_dwordx4 v[224:225], off
	v_lshl_add_u64 v[224:225], s[42:43], 0, v[148:149]
	s_mov_b32 m0, s53
	s_nop 0
	global_load_lds_dwordx4 v[224:225], off
	s_waitcnt vmcnt(8)
	s_waitcnt lgkmcnt(0)
	v_mfma_f32_16x16x32_bf16 v[128:131], v[132:135], v[178:181], v[128:131]
	v_mfma_f32_16x16x32_bf16 v[124:127], v[140:143], v[178:181], v[124:127]
	v_mfma_f32_16x16x32_bf16 v[112:115], v[132:135], v[186:189], v[112:115]
	v_mfma_f32_16x16x32_bf16 v[108:111], v[140:143], v[186:189], v[108:111]
	s_barrier
	s_setprio 1
	v_mfma_f32_16x16x32_bf16 v[96:99], v[132:135], v[202:205], v[96:99]
	v_mfma_f32_16x16x32_bf16 v[92:95], v[140:143], v[202:205], v[92:95]
	v_mfma_f32_16x16x32_bf16 v[80:83], v[132:135], v[210:213], v[80:83]
	v_mfma_f32_16x16x32_bf16 v[76:79], v[140:143], v[210:213], v[76:79]
	v_mfma_f32_16x16x32_bf16 v[128:131], v[136:139], v[182:185], v[128:131]
	v_mfma_f32_16x16x32_bf16 v[124:127], v[144:147], v[182:185], v[124:127]
	v_mfma_f32_16x16x32_bf16 v[112:115], v[136:139], v[190:193], v[112:115]
	v_mfma_f32_16x16x32_bf16 v[108:111], v[144:147], v[190:193], v[108:111]
	v_mfma_f32_16x16x32_bf16 v[96:99], v[136:139], v[206:209], v[96:99]
	v_mfma_f32_16x16x32_bf16 v[92:95], v[144:147], v[206:209], v[92:95]
	v_mfma_f32_16x16x32_bf16 v[80:83], v[136:139], v[214:217], v[80:83]
	v_mfma_f32_16x16x32_bf16 v[76:79], v[144:147], v[214:217], v[76:79]
	s_setprio 0
	s_setprio 1
	v_mfma_f32_16x16x32_bf16 v[120:123], v[158:161], v[178:181], v[120:123]
	v_mfma_f32_16x16x32_bf16 v[116:119], v[166:169], v[178:181], v[116:119]
	v_mfma_f32_16x16x32_bf16 v[104:107], v[158:161], v[186:189], v[104:107]
	v_mfma_f32_16x16x32_bf16 v[100:103], v[166:169], v[186:189], v[100:103]
	v_mfma_f32_16x16x32_bf16 v[88:91], v[158:161], v[202:205], v[88:91]
	v_mfma_f32_16x16x32_bf16 v[84:87], v[166:169], v[202:205], v[84:87]
	v_mfma_f32_16x16x32_bf16 v[72:75], v[158:161], v[210:213], v[72:75]
	v_mfma_f32_16x16x32_bf16 v[68:71], v[166:169], v[210:213], v[68:71]
	v_mfma_f32_16x16x32_bf16 v[120:123], v[162:165], v[182:185], v[120:123]
	v_mfma_f32_16x16x32_bf16 v[116:119], v[174:177], v[182:185], v[116:119]
	v_mfma_f32_16x16x32_bf16 v[104:107], v[162:165], v[190:193], v[104:107]
	v_mfma_f32_16x16x32_bf16 v[100:103], v[174:177], v[190:193], v[100:103]
	v_mfma_f32_16x16x32_bf16 v[88:91], v[162:165], v[206:209], v[88:91]
	v_mfma_f32_16x16x32_bf16 v[84:87], v[174:177], v[206:209], v[84:87]
	v_mfma_f32_16x16x32_bf16 v[72:75], v[162:165], v[214:217], v[72:75]
	v_mfma_f32_16x16x32_bf16 v[68:71], v[174:177], v[214:217], v[68:71]
	s_setprio 0
	s_barrier
; #define PG8_STAGE(bufoff, gbase, voff) do { _Pragma("unroll") for (int _i = 0; _i < 2; ++_i) \
;         __builtin_amdgcn_global_load_lds((const unsigned*)((const char*)(gbase) + (voff)[_i]), (PG8_LAS unsigned*)(lds + (bufoff) + ldsw + _i * 8192), 16, 0, 0); } while (0)
; #define PG8_LDA(dst, b, h) do { _Pragma("unroll") for (int m = 0; m < 4; ++m) _Pragma("unroll") for (int k = 0; k < 2; ++k) dst[m][k] = *(const PG8_LAS bf16x8*)(lds + PG8_SA(b, h) + aoff + m * 2048 + k * 1024); } while (0)
; #define PG8_MMA(ai, bj, At, Bt) do { __builtin_amdgcn_s_setprio(1); _Pragma("unroll") for (int m = 0; m < 4; ++m) _Pragma("unroll") for (int n = 0; n < 2; ++n) _Pragma("unroll") for (int k = 0; k < 2; ++k) \
;         acc[ai][bj][m][n] = __builtin_amdgcn_mfma_f32_16x16x32_bf16(Bt[n][k], At[m][k], acc[ai][bj][m][n], 0, 0, 0); __builtin_amdgcn_s_setprio(0); } while (0)
; #define PG8_WAIT_V(n) asm volatile("s_waitcnt vmcnt(" #n ")" ::: "memory")
; #define PG8_WAIT_L(n) asm volatile("s_waitcnt lgkmcnt(" #n ")" ::: "memory")
; #define PG8_BAR __builtin_amdgcn_s_barrier()
; #define PG8_SCHED __builtin_amdgcn_sched_barrier(0)
; template <class Epi, class Sched, bool ALIGN_EPI = false, bool SP2 = false>
; __device__ __forceinline__ void gemm_phase(PG8_LAS unsigned char* lds, const Gemm g, const Sched& S, const Epi& E) {
;     ...
;             PG8_LDA(At, 1, 1); PG8_STAGE(PG8_SB(1, 0), b3, voffB); PG8_STAGE(PG8_SB(1, 1), b3 + hstep, voffB); PG8_STAGE(PG8_SA(1, 0), a3, voffA);
;             PG8_WAIT_V(8); PG8_WAIT_L(0); PG8_BAR; PG8_MMA(1, 0, At, B0); PG8_MMA(1, 1, At, B1); PG8_BAR; PG8_SCHED;
	s_add_i32 s42, s60, s49
	v_lshl_add_u64 v[194:195], v[194:195], 0, s[36:37]
	s_mov_b32 m0, s42
	ds_read_b128 v[178:181], v173 offset:49152
	ds_read_b128 v[182:185], v173 offset:50176
	ds_read_b128 v[186:189], v173 offset:51200
	ds_read_b128 v[190:193], v173 offset:52224
	ds_read_b128 v[202:205], v173 offset:53248
	ds_read_b128 v[206:209], v173 offset:54272
	ds_read_b128 v[210:213], v173 offset:55296
	ds_read_b128 v[214:217], v173 offset:56320
	global_load_lds_dwordx4 v[194:195], off
	s_add_i32 m0, s42, 0x2000
	s_add_u32 s4, s4, 0x40080
	v_lshl_add_u64 v[194:195], v[218:219], 0, s[36:37]
	s_addc_u32 s5, s5, 0
	s_add_i32 s42, s61, s49
	global_load_lds_dwordx4 v[194:195], off
	v_lshl_add_u64 v[194:195], s[4:5], 0, v[150:151]
	s_mov_b32 m0, s42
	s_nop 0
	global_load_lds_dwordx4 v[194:195], off
	v_lshl_add_u64 v[194:195], s[4:5], 0, v[32:33]
	s_add_i32 m0, s42, 0x2000
	s_nop 0
	global_load_lds_dwordx4 v[194:195], off
	v_lshl_add_u64 v[194:195], v[220:221], 0, s[36:37]
	s_mov_b32 m0, s54
	s_nop 0
	global_load_lds_dwordx4 v[194:195], off
	v_lshl_add_u64 v[194:195], v[222:223], 0, s[36:37]
	s_mov_b32 m0, s55
	s_nop 0
	global_load_lds_dwordx4 v[194:195], off
	s_waitcnt vmcnt(8)
	s_waitcnt lgkmcnt(0)
	v_mfma_f32_16x16x32_bf16 v[64:67], v[132:135], v[178:181], v[64:67]
	v_mfma_f32_16x16x32_bf16 v[60:63], v[140:143], v[178:181], v[60:63]
	v_mfma_f32_16x16x32_bf16 v[48:51], v[132:135], v[186:189], v[48:51]
	v_mfma_f32_16x16x32_bf16 v[44:47], v[140:143], v[186:189], v[44:47]
	s_barrier
	s_setprio 1
	v_mfma_f32_16x16x32_bf16 v[28:31], v[132:135], v[202:205], v[28:31]
	v_mfma_f32_16x16x32_bf16 v[24:27], v[140:143], v[202:205], v[24:27]
	v_mfma_f32_16x16x32_bf16 v[12:15], v[132:135], v[210:213], v[12:15]
	v_mfma_f32_16x16x32_bf16 v[8:11], v[140:143], v[210:213], v[8:11]
	v_mfma_f32_16x16x32_bf16 v[64:67], v[136:139], v[182:185], v[64:67]
	v_mfma_f32_16x16x32_bf16 v[60:63], v[144:147], v[182:185], v[60:63]
	v_mfma_f32_16x16x32_bf16 v[48:51], v[136:139], v[190:193], v[48:51]
	v_mfma_f32_16x16x32_bf16 v[44:47], v[144:147], v[190:193], v[44:47]
	v_mfma_f32_16x16x32_bf16 v[28:31], v[136:139], v[206:209], v[28:31]
	v_mfma_f32_16x16x32_bf16 v[24:27], v[144:147], v[206:209], v[24:27]
	v_mfma_f32_16x16x32_bf16 v[12:15], v[136:139], v[214:217], v[12:15]
	v_mfma_f32_16x16x32_bf16 v[8:11], v[144:147], v[214:217], v[8:11]
	s_setprio 0
	s_setprio 1
	v_mfma_f32_16x16x32_bf16 v[56:59], v[158:161], v[178:181], v[56:59]
	v_mfma_f32_16x16x32_bf16 v[52:55], v[166:169], v[178:181], v[52:55]
	v_mfma_f32_16x16x32_bf16 v[40:43], v[158:161], v[186:189], v[40:43]
	v_mfma_f32_16x16x32_bf16 v[36:39], v[166:169], v[186:189], v[36:39]
	v_mfma_f32_16x16x32_bf16 v[20:23], v[158:161], v[202:205], v[20:23]
	v_mfma_f32_16x16x32_bf16 v[16:19], v[166:169], v[202:205], v[16:19]
	v_mfma_f32_16x16x32_bf16 v[4:7], v[158:161], v[210:213], v[4:7]
	v_mfma_f32_16x16x32_bf16 v[0:3], v[166:169], v[210:213], v[0:3]
	v_mfma_f32_16x16x32_bf16 v[56:59], v[162:165], v[182:185], v[56:59]
	v_mfma_f32_16x16x32_bf16 v[52:55], v[174:177], v[182:185], v[52:55]
	v_mfma_f32_16x16x32_bf16 v[40:43], v[162:165], v[190:193], v[40:43]
	v_mfma_f32_16x16x32_bf16 v[36:39], v[174:177], v[190:193], v[36:39]
	v_mfma_f32_16x16x32_bf16 v[20:23], v[162:165], v[206:209], v[20:23]
	v_mfma_f32_16x16x32_bf16 v[16:19], v[174:177], v[206:209], v[16:19]
	v_mfma_f32_16x16x32_bf16 v[4:7], v[162:165], v[214:217], v[4:7]
	v_mfma_f32_16x16x32_bf16 v[0:3], v[174:177], v[214:217], v[0:3]
	s_setprio 0
	s_barrier
	s_add_i32 s59, s59, 2
	s_add_u32 s0, s0, 0x100
	s_addc_u32 s1, s1, 0
	s_add_u32 s47, s47, 0x100
	s_addc_u32 s58, s58, 0
	s_cmp_gt_u32 s59, 13
	s_branch .LBB0_342
